# early L1 invalidate in grid barriers + one wave per XCD issues an L2 write-back hint right after its last stores (before the drain wait)
# baseline (speedup 1.0000x reference)
; DI void xcd_barrier(const XcdBarrier& b) {
;     asm volatile("s_waitcnt vmcnt(0)" ::: "memory");
.LBB0_123:
	s_cmp_gt_u32 s2, 7
	s_cbranch_scc1 .Lpf_1_plain
	v_readfirstlane_b32 s100, v196
	s_cmp_lt_u32 s100, 0x1c0
	s_cbranch_scc1 .Lpf_1_plain
	buffer_wbl2 sc1
	s_waitcnt vmcnt(1)
	s_branch .Lpf_1_done

; DI int opaque(int v) { asm volatile("" : "+v"(v)); return v; }
; DI void xcd_barrier(const XcdBarrier& b) {
;     asm volatile("s_waitcnt vmcnt(0)" ::: "memory");
;     __syncthreads();
;     if (opaque((int)threadIdx.x) == 0) {
;         unsigned* bar = b.bar;
;         __builtin_amdgcn_s_waitcnt(0);
;         unsigned nloc = b.st[0], nx = b.st[1];
;         if (nloc == 0u) { xcd_barrier_complete(bar, b.x, nloc, nx); b.st[0] = nloc; b.st[1] = nx; }
.Lpf_1_done:
	v_mov_b32_e32 v0, v196
	s_barrier
	s_nop 0
	v_cmp_eq_u32_e32 vcc, 0, v0
	s_and_saveexec_b64 s[30:31], vcc
	s_cbranch_execz .LBB0_175
	v_readlane_b32 s12, v252, 56
	s_waitcnt vmcnt(0) expcnt(0) lgkmcnt(0)
	s_nop 0
	v_mov_b32_e32 v0, s12
	ds_read_b32 v3, v0
	v_readlane_b32 s12, v252, 54
	s_waitcnt lgkmcnt(0)
	v_cmp_ne_u32_e32 vcc, 0, v3
	v_mov_b32_e32 v0, s12
	ds_read_b32 v2, v0
	s_cbranch_vccnz .LBB0_139
	s_mov_b32 s12, 1
	s_branch .LBB0_127

; DI void xcd_barrier(const XcdBarrier& b) {
;     ...
;     __syncthreads();
.Lpf_2_done:
	s_mov_b64 s[72:73], 0xba00000
	s_barrier

; DI int opaque(int v) { asm volatile("" : "+v"(v)); return v; }
; DI void xcd_barrier(const XcdBarrier& b) {
;     asm volatile("s_waitcnt vmcnt(0)" ::: "memory");
;     __syncthreads();
;     if (opaque((int)threadIdx.x) == 0) {
;         unsigned* bar = b.bar;
;         __builtin_amdgcn_s_waitcnt(0);
;         unsigned nloc = b.st[0], nx = b.st[1];
;         if (nloc == 0u) { xcd_barrier_complete(bar, b.x, nloc, nx); b.st[0] = nloc; b.st[1] = nx; }
.Lpf_6_done:
	v_mov_b32_e32 v0, v196
	s_waitcnt vmcnt(0)
	s_barrier
	s_nop 0
	v_cmp_eq_u32_e32 vcc, 0, v0
	s_and_saveexec_b64 s[30:31], vcc
	s_cbranch_execz .LBB0_798
	v_readlane_b32 s12, v252, 56
	s_waitcnt vmcnt(0) expcnt(0) lgkmcnt(0)
	s_nop 0
	v_mov_b32_e32 v0, s12
	ds_read_b32 v3, v0
	v_readlane_b32 s12, v252, 54
	s_waitcnt lgkmcnt(0)
	v_cmp_ne_u32_e32 vcc, 0, v3
	v_mov_b32_e32 v0, s12
	ds_read_b32 v2, v0
	s_cbranch_vccnz .LBB0_762
	s_mov_b32 s12, 1
	s_branch .LBB0_750

; DI void xcd_barrier(const XcdBarrier& b) {
;     ...
;     __syncthreads();
.Lpf_8_done:
	s_barrier

; DI void xcd_barrier(const XcdBarrier& b) {
;     ...
;     __syncthreads();
.Lpf_9_done:
	s_mov_b32 s66, 0x9a00000
	s_barrier

; DI int opaque(int v) { asm volatile("" : "+v"(v)); return v; }
; DI void xcd_barrier(const XcdBarrier& b) {
;     asm volatile("s_waitcnt vmcnt(0)" ::: "memory");
;     __syncthreads();
;     if (opaque((int)threadIdx.x) == 0) {
;         unsigned* bar = b.bar;
;         __builtin_amdgcn_s_waitcnt(0);
;         unsigned nloc = b.st[0], nx = b.st[1];
;         if (nloc == 0u) { xcd_barrier_complete(bar, b.x, nloc, nx); b.st[0] = nloc; b.st[1] = nx; }
.Lpf_10_done:
	v_mov_b32_e32 v0, v196
	s_waitcnt vmcnt(63) expcnt(7) lgkmcnt(15)
	s_barrier
	s_nop 0
	v_cmp_eq_u32_e32 vcc, 0, v0
	s_and_saveexec_b64 s[30:31], vcc
	s_cbranch_execz .LBB0_1238
	v_readlane_b32 s12, v252, 56
	s_waitcnt vmcnt(0) expcnt(0) lgkmcnt(0)
	s_nop 0
	v_mov_b32_e32 v0, s12
	ds_read_b32 v3, v0
	v_readlane_b32 s12, v252, 54
	s_waitcnt lgkmcnt(0)
	v_cmp_ne_u32_e32 vcc, 0, v3
	v_mov_b32_e32 v0, s12
	ds_read_b32 v2, v0
	s_cbranch_vccnz .LBB0_1202
	s_mov_b32 s12, 1
	s_branch .LBB0_1190

; DI void xcd_barrier(const XcdBarrier& b) {
;     ...
;     __syncthreads();
.Lpf_12_done:
	v_readlane_b32 s66, v251, 8
	s_barrier
	v_readlane_b32 s67, v251, 9
